# memory K/V projection of layer l moved from layer 0 (8th tile round on WGs 192-255) into layer l P1 on otherwise idle WGs 232-247
# baseline (speedup 1.0000x reference)
.LBB0_316:
	v_readlane_b32 s0, v255, 43
	s_cmp_lg_u32 s0, 0
	v_readlane_b32 s63, v253, 59
	v_readlane_b32 s65, v253, 58
	v_readlane_b32 s1, v255, 44
	s_branch .LBB0_327

.LBB0_327:
	v_readlane_b32 s92, v255, 43
	s_branch .LBB0_330
.LBB0_328:
	s_waitcnt vmcnt(0)
	v_readlane_b32 s20, v255, 39
	s_movk_i32 s83, 0x7f
	s_barrier
.LBB0_329:
	s_branch .LBB0_317
.LBB0_330:
	s_mov_b32 s1, 40
	s_sub_i32 s1, s56, s1
	s_ashr_i32 s3, s1, 31
	s_abs_i32 s1, s1
	s_mul_hi_u32 s4, s1, s58
	s_mul_i32 s4, s4, s57
	s_sub_i32 s1, s1, s4
	s_sub_i32 s4, s1, s57
	s_cmp_ge_u32 s1, s57
	s_cselect_b32 s1, s4, s1
	s_sub_i32 s4, s1, s57
	s_cmp_ge_u32 s1, s57
	s_cselect_b32 s1, s4, s1
	s_xor_b32 s1, s1, s3
	s_movk_i32 s0, 0x400
	s_sub_i32 s3, s1, s3
	v_mov_b32_e32 v18, v193
	s_cmp_gt_i32 s3, 15
	v_readfirstlane_b32 s14, v18
	s_cbranch_scc1 .LBB0_329
	s_ashr_i32 s16, s3, 31
	s_lshr_b32 s1, s16, 29
	s_add_i32 s6, s3, s1
	s_and_b32 s1, s6, -8
	s_sub_i32 s1, s3, s1
	s_cmp_gt_i32 s1, -1
	s_mov_b64 s[4:5], -1
	s_cbranch_scc0 .LBB0_333
	s_lshl_b32 s8, s1, 1
	s_mov_b64 s[4:5], 0
